# mlstm_out inter-chunk fragment loads pipelined 4 deep, output-gate epilogue and ssd_out final block loads issued one step ahead
# speedup vs baseline: 1.0964x; 1.0074x over previous
.LBB0_592:
	s_or_b64 exec, exec, s[4:5]
	v_mul_u32_u24_e32 v6, 0x1b00, v69
	s_lshl_b32 s30, s6, 1
	v_readlane_b32 s2, v240, 38
	v_lshlrev_b32_e32 v168, 1, v6
	v_or_b32_e32 v6, s70, v69
	v_or_b32_e32 v4, v72, v71
	v_readlane_b32 s3, v240, 39
	s_add_u32 s2, s2, s30
	v_ashrrev_i32_e32 v7, 31, v6
	s_addc_u32 s3, s3, 0
	v_ashrrev_i32_e32 v5, 31, v4
	v_lshl_add_u64 v[12:13], s[28:29], 0, v[168:169]
	v_lshlrev_b64 v[6:7], 12, v[6:7]
	v_lshl_add_u64 v[50:51], s[2:3], 0, v[6:7]
	v_lshlrev_b64 v[6:7], 1, v[4:5]
	v_lshl_add_u64 v[12:13], v[12:13], 0, s[30:31]
	v_lshl_add_u64 v[12:13], v[12:13], 0, v[6:7]
	v_add_co_u32_e32 v42, vcc, s63, v12
	s_waitcnt lgkmcnt(0)
	s_nop 0
	v_addc_co_u32_e32 v43, vcc, 0, v13, vcc
	s_barrier
	global_load_dwordx2 v[54:55], v[42:43], off offset:2048
	v_mov_b32_e32 v252, v42
	v_mov_b32_e32 v253, v43
	s_lshl_b32 s4, s6, 2
	s_add_u32 s4, s56, s4
	s_addc_u32 s5, s58, 0
	v_lshl_add_u64 v[4:5], v[4:5], 2, s[4:5]
	global_load_dwordx4 v[42:45], v[4:5], off
	global_load_dwordx2 v[244:245], v[252:253], off offset:2080
	global_load_dwordx4 v[248:251], v[4:5], off offset:64
	ds_read_b32 v46, v46 offset:256
	v_lshl_add_u64 v[52:53], v[12:13], 0, s[34:35]
	s_mov_b64 s[4:5], 0x37800
	s_add_i32 s88, s88, s69
	s_add_i32 s86, s86, s69
	s_cmpk_gt_i32 s88, 0x1ff
	s_waitcnt vmcnt(1)
	v_lshlrev_b32_e32 v47, 16, v54
	v_mul_f32_e32 v47, 0xbfb8aa3b, v47
	v_exp_f32_e32 v47, v47
	s_nop 0
	v_add_f32_e32 v47, 1.0, v47
	v_rcp_f32_e32 v58, v47
	v_and_b32_e32 v47, 0xffff0000, v54
	v_mul_f32_e32 v47, 0xbfb8aa3b, v47
	v_exp_f32_e32 v47, v47
	s_nop 0
	v_add_f32_e32 v47, 1.0, v47
	v_rcp_f32_e32 v59, v47
	s_waitcnt lgkmcnt(0)
	v_pk_mul_f32 v[36:37], v[36:37], v[46:47] op_sel_hi:[1,0]
	v_pk_mul_f32 v[34:35], v[34:35], v[46:47] op_sel_hi:[1,0]
	s_waitcnt vmcnt(0)
	v_pk_mul_f32 v[36:37], v[36:37], v[42:43]
	v_pk_mul_f32 v[34:35], v[34:35], v[44:45]
	v_pk_mul_f32 v[36:37], v[36:37], v[58:59]
	s_nop 0
	v_cvt_pk_bf16_f32 v36, v36, v37
	v_lshlrev_b32_e32 v37, 16, v55
	v_mul_f32_e32 v37, 0xbfb8aa3b, v37
	v_exp_f32_e32 v37, v37
	s_nop 0
	v_add_f32_e32 v37, 1.0, v37
	v_rcp_f32_e32 v42, v37
	v_and_b32_e32 v37, 0xffff0000, v55
	v_mul_f32_e32 v37, 0xbfb8aa3b, v37
	v_exp_f32_e32 v37, v37
	s_nop 0
	v_add_f32_e32 v37, 1.0, v37
	v_rcp_f32_e32 v43, v37
	s_nop 0
	v_pk_mul_f32 v[34:35], v[34:35], v[42:43]
	s_nop 0
	v_cvt_pk_bf16_f32 v37, v34, v35
	v_lshl_add_u64 v[42:43], v[50:51], 0, v[6:7]
	global_store_dwordx2 v[42:43], v[36:37], off
	s_waitcnt vmcnt(2)
	v_mov_b32_e32 v44, v244
	v_mov_b32_e32 v45, v245
	s_nop 0
	s_waitcnt vmcnt(1)
	v_mov_b32_e32 v34, v248
	v_mov_b32_e32 v35, v249
	v_mov_b32_e32 v36, v250
	v_mov_b32_e32 v37, v251
	v_add_co_u32_e32 v252, vcc, 0x36000, v252
	s_nop 1
	v_addc_co_u32_e32 v253, vcc, 0, v253, vcc
	global_load_dwordx2 v[244:245], v[252:253], off offset:2048
	global_load_dwordx4 v[248:251], v[4:5], off
	v_lshlrev_b32_e32 v47, 16, v44
	v_and_b32_e32 v44, 0xffff0000, v44
	v_mul_f32_e32 v47, 0xbfb8aa3b, v47
	v_mul_f32_e32 v44, 0xbfb8aa3b, v44
	v_exp_f32_e32 v47, v47
	v_exp_f32_e32 v44, v44
	v_add_f32_e32 v47, 1.0, v47
	v_add_f32_e32 v44, 1.0, v44
	v_rcp_f32_e32 v50, v47
	v_rcp_f32_e32 v51, v44
	v_pk_mul_f32 v[32:33], v[32:33], v[46:47] op_sel_hi:[1,0]
	v_pk_mul_f32 v[30:31], v[30:31], v[46:47] op_sel_hi:[1,0]
	v_pk_mul_f32 v[32:33], v[32:33], v[34:35]
	v_pk_mul_f32 v[30:31], v[30:31], v[36:37]
	v_pk_mul_f32 v[32:33], v[32:33], v[50:51]
	s_nop 0
	v_cvt_pk_bf16_f32 v32, v32, v33
	v_lshlrev_b32_e32 v33, 16, v45
	v_mul_f32_e32 v33, 0xbfb8aa3b, v33
	v_exp_f32_e32 v33, v33
	s_nop 0
	v_add_f32_e32 v33, 1.0, v33
	v_rcp_f32_e32 v34, v33
	v_and_b32_e32 v33, 0xffff0000, v45
	v_mul_f32_e32 v33, 0xbfb8aa3b, v33
	v_exp_f32_e32 v33, v33
	s_nop 0
	v_add_f32_e32 v33, 1.0, v33
	v_rcp_f32_e32 v35, v33
	s_nop 0
	v_pk_mul_f32 v[30:31], v[30:31], v[34:35]
	s_nop 0
	v_cvt_pk_bf16_f32 v33, v30, v31
	v_or_b32_e32 v30, s70, v56
	v_ashrrev_i32_e32 v31, 31, v30
	global_store_dwordx2 v[42:43], v[32:33], off offset:32
	v_lshlrev_b64 v[30:31], 12, v[30:31]
	v_lshl_add_u64 v[42:43], v[12:13], 0, s[4:5]
	s_mov_b32 s4, 0x37000
	v_lshl_add_u64 v[36:37], s[2:3], 0, v[30:31]
	v_add_co_u32_e32 v30, vcc, s4, v12
	ds_read_b32 v34, v41 offset:256
	s_nop 0
	v_addc_co_u32_e32 v31, vcc, 0, v13, vcc
	s_waitcnt vmcnt(2)
	v_mov_b32_e32 v44, v244
	v_mov_b32_e32 v45, v245
	s_nop 0
	s_waitcnt vmcnt(1)
	v_mov_b32_e32 v30, v248
	v_mov_b32_e32 v31, v249
	v_mov_b32_e32 v32, v250
	v_mov_b32_e32 v33, v251
	global_load_dwordx2 v[244:245], v[252:253], off offset:2080
	global_load_dwordx4 v[248:251], v[4:5], off offset:64
	s_mov_b64 s[4:5], 0x6d800
	v_lshlrev_b32_e32 v35, 16, v44
	v_mul_f32_e32 v35, 0xbfb8aa3b, v35
	v_exp_f32_e32 v35, v35
	s_nop 0
	v_add_f32_e32 v35, 1.0, v35
	v_rcp_f32_e32 v46, v35
	v_and_b32_e32 v35, 0xffff0000, v44
	v_mul_f32_e32 v35, 0xbfb8aa3b, v35
	v_exp_f32_e32 v35, v35
	s_nop 0
	v_add_f32_e32 v35, 1.0, v35
	v_rcp_f32_e32 v47, v35
	s_waitcnt lgkmcnt(0)
	v_pk_mul_f32 v[28:29], v[28:29], v[34:35] op_sel_hi:[1,0]
	v_pk_mul_f32 v[26:27], v[26:27], v[34:35] op_sel_hi:[1,0]
	v_pk_mul_f32 v[28:29], v[28:29], v[30:31]
	v_pk_mul_f32 v[26:27], v[26:27], v[32:33]
	v_pk_mul_f32 v[28:29], v[28:29], v[46:47]
	s_nop 0
	v_cvt_pk_bf16_f32 v28, v28, v29
	v_lshlrev_b32_e32 v29, 16, v45
	v_mul_f32_e32 v29, 0xbfb8aa3b, v29
	v_exp_f32_e32 v29, v29
	s_nop 0
	v_add_f32_e32 v29, 1.0, v29
	v_rcp_f32_e32 v30, v29
	v_and_b32_e32 v29, 0xffff0000, v45
	v_mul_f32_e32 v29, 0xbfb8aa3b, v29
	v_exp_f32_e32 v29, v29
	s_nop 0
	v_add_f32_e32 v29, 1.0, v29
	v_rcp_f32_e32 v31, v29
	s_nop 0
	v_pk_mul_f32 v[26:27], v[26:27], v[30:31]
	s_nop 0
	v_cvt_pk_bf16_f32 v29, v26, v27
	v_lshl_add_u64 v[30:31], v[36:37], 0, v[6:7]
	global_store_dwordx2 v[30:31], v[28:29], off
	s_waitcnt vmcnt(2)
	v_mov_b32_e32 v32, v244
	v_mov_b32_e32 v33, v245
	s_nop 0
	s_waitcnt vmcnt(1)
	v_mov_b32_e32 v26, v248
	v_mov_b32_e32 v27, v249
	v_mov_b32_e32 v28, v250
	v_mov_b32_e32 v29, v251
	v_add_co_u32_e32 v252, vcc, 0x36000, v252
	s_nop 1
	v_addc_co_u32_e32 v253, vcc, 0, v253, vcc
	global_load_dwordx2 v[244:245], v[252:253], off offset:2048
	global_load_dwordx4 v[248:251], v[4:5], off
	v_lshlrev_b32_e32 v35, 16, v32
	v_and_b32_e32 v32, 0xffff0000, v32
	v_mul_f32_e32 v35, 0xbfb8aa3b, v35
	v_mul_f32_e32 v32, 0xbfb8aa3b, v32
	v_exp_f32_e32 v35, v35
	v_exp_f32_e32 v32, v32
	v_add_f32_e32 v35, 1.0, v35
	v_add_f32_e32 v32, 1.0, v32
	v_rcp_f32_e32 v36, v35
	v_rcp_f32_e32 v37, v32
	v_pk_mul_f32 v[24:25], v[24:25], v[34:35] op_sel_hi:[1,0]
	v_pk_mul_f32 v[22:23], v[22:23], v[34:35] op_sel_hi:[1,0]
	v_pk_mul_f32 v[24:25], v[24:25], v[26:27]
	v_pk_mul_f32 v[22:23], v[22:23], v[28:29]
	v_pk_mul_f32 v[24:25], v[24:25], v[36:37]
	s_nop 0
	v_cvt_pk_bf16_f32 v24, v24, v25
	v_lshlrev_b32_e32 v25, 16, v33
	v_mul_f32_e32 v25, 0xbfb8aa3b, v25
	v_exp_f32_e32 v25, v25
	s_nop 0
	v_add_f32_e32 v25, 1.0, v25
	v_rcp_f32_e32 v26, v25
	v_and_b32_e32 v25, 0xffff0000, v33
	v_mul_f32_e32 v25, 0xbfb8aa3b, v25
	v_exp_f32_e32 v25, v25
	s_nop 0
	v_add_f32_e32 v25, 1.0, v25
	v_rcp_f32_e32 v27, v25
	s_nop 0
	v_pk_mul_f32 v[22:23], v[22:23], v[26:27]
	s_nop 0
	v_cvt_pk_bf16_f32 v25, v22, v23
	v_or_b32_e32 v22, s70, v48
	v_ashrrev_i32_e32 v23, 31, v22
	global_store_dwordx2 v[30:31], v[24:25], off offset:32
	v_lshlrev_b64 v[22:23], 12, v[22:23]
	v_lshl_add_u64 v[30:31], v[12:13], 0, s[4:5]
	s_mov_b32 s4, 0x6d000
	v_lshl_add_u64 v[28:29], s[2:3], 0, v[22:23]
	v_add_co_u32_e32 v22, vcc, s4, v12
	ds_read_b32 v26, v39 offset:256
	s_nop 0
	v_addc_co_u32_e32 v23, vcc, 0, v13, vcc
	s_waitcnt vmcnt(2)
	v_mov_b32_e32 v32, v244
	v_mov_b32_e32 v33, v245
	s_nop 0
	s_waitcnt vmcnt(1)
	v_mov_b32_e32 v22, v248
	v_mov_b32_e32 v23, v249
	v_mov_b32_e32 v24, v250
	v_mov_b32_e32 v25, v251
	global_load_dwordx2 v[244:245], v[252:253], off offset:2080
	global_load_dwordx4 v[248:251], v[4:5], off offset:64
	v_lshlrev_b32_e32 v27, 16, v32
	v_mul_f32_e32 v27, 0xbfb8aa3b, v27
	v_exp_f32_e32 v27, v27
	s_nop 0
	v_add_f32_e32 v27, 1.0, v27
	v_rcp_f32_e32 v34, v27
	v_and_b32_e32 v27, 0xffff0000, v32
	v_mul_f32_e32 v27, 0xbfb8aa3b, v27
	v_exp_f32_e32 v27, v27
	s_nop 0
	v_add_f32_e32 v27, 1.0, v27
	v_rcp_f32_e32 v35, v27
	s_waitcnt lgkmcnt(0)
	v_pk_mul_f32 v[20:21], v[20:21], v[26:27] op_sel_hi:[1,0]
	v_pk_mul_f32 v[18:19], v[18:19], v[26:27] op_sel_hi:[1,0]
	v_pk_mul_f32 v[20:21], v[20:21], v[22:23]
	v_pk_mul_f32 v[18:19], v[18:19], v[24:25]
	v_pk_mul_f32 v[20:21], v[20:21], v[34:35]
	s_nop 0
	v_cvt_pk_bf16_f32 v20, v20, v21
	v_lshlrev_b32_e32 v21, 16, v33
	v_mul_f32_e32 v21, 0xbfb8aa3b, v21
	v_exp_f32_e32 v21, v21
	s_nop 0
	v_add_f32_e32 v21, 1.0, v21
	v_rcp_f32_e32 v22, v21
	v_and_b32_e32 v21, 0xffff0000, v33
	v_mul_f32_e32 v21, 0xbfb8aa3b, v21
	v_exp_f32_e32 v21, v21
	s_nop 0
	v_add_f32_e32 v21, 1.0, v21
	v_rcp_f32_e32 v23, v21
	s_nop 0
	v_pk_mul_f32 v[18:19], v[18:19], v[22:23]
	s_nop 0
	v_cvt_pk_bf16_f32 v21, v18, v19
	v_lshl_add_u64 v[22:23], v[28:29], 0, v[6:7]
	global_store_dwordx2 v[22:23], v[20:21], off
	s_waitcnt vmcnt(2)
	v_mov_b32_e32 v24, v244
	v_mov_b32_e32 v25, v245
	s_nop 0
	s_waitcnt vmcnt(1)
	v_mov_b32_e32 v18, v248
	v_mov_b32_e32 v19, v249
	v_mov_b32_e32 v20, v250
	v_mov_b32_e32 v21, v251
	v_add_co_u32_e32 v252, vcc, 0x36000, v252
	s_nop 1
	v_addc_co_u32_e32 v253, vcc, 0, v253, vcc
	global_load_dwordx2 v[244:245], v[252:253], off offset:2048
	global_load_dwordx4 v[248:251], v[4:5], off
	v_lshlrev_b32_e32 v27, 16, v24
	v_and_b32_e32 v24, 0xffff0000, v24
	v_mul_f32_e32 v27, 0xbfb8aa3b, v27
	v_mul_f32_e32 v24, 0xbfb8aa3b, v24
	v_exp_f32_e32 v27, v27
	v_exp_f32_e32 v24, v24
	v_add_f32_e32 v27, 1.0, v27
	v_add_f32_e32 v24, 1.0, v24
	v_rcp_f32_e32 v28, v27
	v_rcp_f32_e32 v29, v24
	v_pk_mul_f32 v[16:17], v[16:17], v[26:27] op_sel_hi:[1,0]
	v_pk_mul_f32 v[14:15], v[14:15], v[26:27] op_sel_hi:[1,0]
	v_pk_mul_f32 v[16:17], v[16:17], v[18:19]
	v_pk_mul_f32 v[14:15], v[14:15], v[20:21]
	v_pk_mul_f32 v[16:17], v[16:17], v[28:29]
	s_nop 0
	v_cvt_pk_bf16_f32 v16, v16, v17
	v_lshlrev_b32_e32 v17, 16, v25
	v_mul_f32_e32 v17, 0xbfb8aa3b, v17
	v_exp_f32_e32 v17, v17
	s_nop 0
	v_add_f32_e32 v17, 1.0, v17
	v_rcp_f32_e32 v18, v17
	v_and_b32_e32 v17, 0xffff0000, v25
	v_mul_f32_e32 v17, 0xbfb8aa3b, v17
	v_exp_f32_e32 v17, v17
	s_nop 0
	v_add_f32_e32 v17, 1.0, v17
	v_rcp_f32_e32 v19, v17
	s_nop 0
	v_pk_mul_f32 v[14:15], v[14:15], v[18:19]
	s_nop 0
	v_cvt_pk_bf16_f32 v17, v14, v15
	global_store_dwordx2 v[22:23], v[16:17], off offset:32
	v_or_b32_e32 v16, s70, v40
	v_ashrrev_i32_e32 v17, 31, v16
	v_lshlrev_b64 v[16:17], 12, v[16:17]
	v_lshl_add_u64 v[18:19], s[2:3], 0, v[16:17]
	s_mov_b64 s[2:3], 0xa3800
	v_lshl_add_u64 v[16:17], v[12:13], 0, s[2:3]
	s_mov_b32 s2, 0xa3000
	v_add_co_u32_e32 v12, vcc, s2, v12
	ds_read_b32 v14, v38 offset:256
	s_nop 0
	v_addc_co_u32_e32 v13, vcc, 0, v13, vcc
	s_waitcnt vmcnt(2)
	v_mov_b32_e32 v12, v244
	v_mov_b32_e32 v13, v245
	s_nop 0
	s_waitcnt vmcnt(1)
	v_mov_b32_e32 v20, v248
	v_mov_b32_e32 v21, v249
	v_mov_b32_e32 v22, v250
	v_mov_b32_e32 v23, v251
	global_load_dwordx2 v[244:245], v[252:253], off offset:2080
	global_load_dwordx4 v[248:251], v[4:5], off offset:64
	v_lshlrev_b32_e32 v15, 16, v12
	v_and_b32_e32 v12, 0xffff0000, v12
	v_mul_f32_e32 v15, 0xbfb8aa3b, v15
	v_mul_f32_e32 v12, 0xbfb8aa3b, v12
	v_exp_f32_e32 v15, v15
	v_exp_f32_e32 v12, v12
	v_add_f32_e32 v15, 1.0, v15
	v_add_f32_e32 v12, 1.0, v12
	v_rcp_f32_e32 v24, v15
	v_rcp_f32_e32 v25, v12
	s_waitcnt lgkmcnt(0)
	v_pk_mul_f32 v[10:11], v[10:11], v[14:15] op_sel_hi:[1,0]
	v_pk_mul_f32 v[8:9], v[8:9], v[14:15] op_sel_hi:[1,0]
	v_pk_mul_f32 v[10:11], v[10:11], v[20:21]
	v_pk_mul_f32 v[8:9], v[8:9], v[22:23]
	v_pk_mul_f32 v[10:11], v[10:11], v[24:25]
	v_pk_mul_f32 v[2:3], v[2:3], v[14:15] op_sel_hi:[1,0]
	v_cvt_pk_bf16_f32 v10, v10, v11
	v_lshlrev_b32_e32 v11, 16, v13
	v_mul_f32_e32 v11, 0xbfb8aa3b, v11
	v_exp_f32_e32 v11, v11
	v_pk_mul_f32 v[0:1], v[0:1], v[14:15] op_sel_hi:[1,0]
	v_add_f32_e32 v11, 1.0, v11
	v_rcp_f32_e32 v12, v11
	v_and_b32_e32 v11, 0xffff0000, v13
	v_mul_f32_e32 v11, 0xbfb8aa3b, v11
	v_exp_f32_e32 v11, v11
	s_nop 0
	v_add_f32_e32 v11, 1.0, v11
	v_rcp_f32_e32 v13, v11
	s_nop 0
	v_pk_mul_f32 v[8:9], v[8:9], v[12:13]
	s_nop 0
	v_cvt_pk_bf16_f32 v11, v8, v9
	v_lshl_add_u64 v[8:9], v[18:19], 0, v[6:7]
	global_store_dwordx2 v[8:9], v[10:11], off
	s_waitcnt vmcnt(2)
	v_mov_b32_e32 v10, v244
	v_mov_b32_e32 v11, v245
	s_nop 0
	s_waitcnt vmcnt(1)
	v_mov_b32_e32 v4, v248
	v_mov_b32_e32 v5, v249
	v_mov_b32_e32 v6, v250
	v_mov_b32_e32 v7, v251
	v_lshlrev_b32_e32 v12, 16, v10
	v_and_b32_e32 v10, 0xffff0000, v10
	v_mul_f32_e32 v12, 0xbfb8aa3b, v12
	v_mul_f32_e32 v10, 0xbfb8aa3b, v10
	v_exp_f32_e32 v12, v12
	v_exp_f32_e32 v10, v10
	v_pk_mul_f32 v[2:3], v[2:3], v[4:5]
	v_pk_mul_f32 v[0:1], v[0:1], v[6:7]
	v_add_f32_e32 v12, 1.0, v12
	v_add_f32_e32 v10, 1.0, v10
	v_rcp_f32_e32 v12, v12
	v_rcp_f32_e32 v13, v10
	s_nop 0
	v_pk_mul_f32 v[2:3], v[2:3], v[12:13]
	s_nop 0
	v_cvt_pk_bf16_f32 v2, v2, v3
	v_lshlrev_b32_e32 v3, 16, v11
	v_mul_f32_e32 v3, 0xbfb8aa3b, v3
	v_exp_f32_e32 v3, v3
	s_nop 0
	v_add_f32_e32 v3, 1.0, v3
	v_rcp_f32_e32 v4, v3
	v_and_b32_e32 v3, 0xffff0000, v11
	v_mul_f32_e32 v3, 0xbfb8aa3b, v3
	v_exp_f32_e32 v3, v3
	s_nop 0
	v_add_f32_e32 v3, 1.0, v3
	v_rcp_f32_e32 v5, v3
	s_nop 0
	v_pk_mul_f32 v[0:1], v[0:1], v[4:5]
	s_nop 0
	v_cvt_pk_bf16_f32 v3, v0, v1
	global_store_dwordx2 v[8:9], v[2:3], off offset:32
	s_barrier
	s_cbranch_scc1 .LBB0_647

.LBB0_603:
	s_or_b64 exec, exec, s[2:3]
	v_lshlrev_b32_e32 v0, 4, v68
	v_ashrrev_i32_e32 v5, 5, v68
	v_mov_b64_e32 v[8:9], s[28:29]
	v_and_b32_e32 v168, 0x1f0, v0
	v_mad_i64_i32 v[0:1], s[2:3], v5, s54, v[8:9]
	s_lshl_b32 s30, s71, 9
	v_lshl_add_u64 v[0:1], v[0:1], 0, s[30:31]
	v_lshl_add_u64 v[10:11], v[0:1], 0, v[168:169]
	v_add_co_u32_e32 v248, vcc, 0x800, v10
	s_nop 1
	v_addc_co_u32_e32 v249, vcc, 0, v11, vcc
	global_load_dwordx4 v[244:247], v[248:249], off offset:2048
	v_add_co_u32_e32 v248, vcc, 0x36000, v248
	s_nop 1
	v_addc_co_u32_e32 v249, vcc, 0, v249, vcc
	global_load_dwordx4 v[244:247], v[248:249], off offset:-2048
	global_load_dwordx4 v[244:247], v[248:249], off
	global_load_dwordx4 v[244:247], v[248:249], off offset:2048
	v_add_co_u32_e32 v248, vcc, 0x36000, v248
	s_nop 1
	v_addc_co_u32_e32 v249, vcc, 0, v249, vcc
	global_load_dwordx4 v[244:247], v[248:249], off offset:-2048
	global_load_dwordx4 v[244:247], v[248:249], off
	global_load_dwordx4 v[244:247], v[248:249], off offset:2048
	v_add_co_u32_e32 v248, vcc, 0x36000, v248
	s_nop 1
	v_addc_co_u32_e32 v249, vcc, 0, v249, vcc
	global_load_dwordx4 v[244:247], v[248:249], off offset:-2048
	global_load_dwordx4 v[244:247], v[248:249], off
	global_load_dwordx4 v[244:247], v[248:249], off offset:2048
	global_load_dwordx4 v[0:3], v[10:11], off
	v_add_u32_e32 v4, 0, v168
	s_movk_i32 s4, 0x210
	v_mad_u64_u32 v[12:13], s[2:3], v5, s4, v[4:5]
	v_add_u32_e32 v6, s53, v168
	v_ashrrev_i32_e32 v73, 6, v68
	v_and_b32_e32 v69, 15, v68
	v_lshlrev_b32_e32 v71, 5, v73
	s_movk_i32 s8, 0x210
	s_waitcnt vmcnt(0)
	ds_write_b128 v12, v[0:3]
	global_load_dwordx4 v[0:3], v[10:11], off offset:2048
	s_waitcnt vmcnt(0)
	ds_write_b128 v12, v[0:3] offset:33792
	v_add_co_u32_e32 v0, vcc, s63, v10
	v_mad_u64_u32 v[12:13], s[2:3], v5, s64, v[6:7]
	s_nop 0
	v_addc_co_u32_e32 v1, vcc, 0, v11, vcc
	global_load_dwordx4 v[0:3], v[0:1], off
	s_waitcnt vmcnt(0)
	ds_write_b128 v12, v[0:3]
	v_add_u32_e32 v0, 0x200, v68
	v_ashrrev_i32_e32 v5, 5, v0
	v_mad_i64_i32 v[0:1], s[2:3], v5, s54, v[8:9]
	v_lshl_add_u64 v[0:1], v[0:1], 0, s[30:31]
	v_lshl_add_u64 v[10:11], v[0:1], 0, v[168:169]
	global_load_dwordx4 v[0:3], v[10:11], off
	v_mad_u64_u32 v[12:13], s[2:3], v5, s4, v[4:5]
	s_waitcnt vmcnt(0)
	ds_write_b128 v12, v[0:3]
	global_load_dwordx4 v[0:3], v[10:11], off offset:2048
	s_waitcnt vmcnt(0)
	ds_write_b128 v12, v[0:3] offset:33792
	v_add_co_u32_e32 v0, vcc, s63, v10
	v_mad_u64_u32 v[12:13], s[2:3], v5, s64, v[6:7]
	s_nop 0
	v_addc_co_u32_e32 v1, vcc, 0, v11, vcc
	global_load_dwordx4 v[0:3], v[0:1], off
	s_waitcnt vmcnt(0)
	ds_write_b128 v12, v[0:3]
	v_add_u32_e32 v0, 0x400, v68
	v_ashrrev_i32_e32 v5, 5, v0
	v_mad_i64_i32 v[0:1], s[2:3], v5, s54, v[8:9]
	v_lshl_add_u64 v[0:1], v[0:1], 0, s[30:31]
	v_lshl_add_u64 v[10:11], v[0:1], 0, v[168:169]
	global_load_dwordx4 v[0:3], v[10:11], off
	v_mad_u64_u32 v[12:13], s[2:3], v5, s4, v[4:5]
	s_waitcnt vmcnt(0)
	ds_write_b128 v12, v[0:3]
	global_load_dwordx4 v[0:3], v[10:11], off offset:2048
	s_waitcnt vmcnt(0)
	ds_write_b128 v12, v[0:3] offset:33792
	v_add_co_u32_e32 v0, vcc, s63, v10
	v_mad_u64_u32 v[12:13], s[2:3], v5, s64, v[6:7]
	s_nop 0
	v_addc_co_u32_e32 v1, vcc, 0, v11, vcc
	global_load_dwordx4 v[0:3], v[0:1], off
	s_waitcnt vmcnt(0)
	ds_write_b128 v12, v[0:3]
	v_add_u32_e32 v0, 0x600, v68
	v_ashrrev_i32_e32 v7, 5, v0
	v_mad_i64_i32 v[0:1], s[2:3], v7, s54, v[8:9]
	v_lshl_add_u64 v[0:1], v[0:1], 0, s[30:31]
	v_lshl_add_u64 v[8:9], v[0:1], 0, v[168:169]
	global_load_dwordx4 v[0:3], v[8:9], off
	v_mad_u64_u32 v[4:5], s[2:3], v7, s4, v[4:5]
	s_waitcnt vmcnt(0)
	ds_write_b128 v4, v[0:3]
	global_load_dwordx4 v[0:3], v[8:9], off offset:2048
	s_waitcnt vmcnt(0)
	ds_write_b128 v4, v[0:3] offset:33792
	v_add_co_u32_e32 v0, vcc, s63, v8
	v_mad_u64_u32 v[4:5], s[2:3], v7, s64, v[6:7]
	s_nop 0
	v_addc_co_u32_e32 v1, vcc, 0, v9, vcc
	global_load_dwordx4 v[0:3], v[0:1], off
	v_ashrrev_i32_e32 v8, 3, v68
	v_and_or_b32 v9, v71, 32, v69
	v_and_b32_e32 v20, -16, v8
	s_waitcnt vmcnt(0)
	ds_write_b128 v4, v[0:3]
	v_and_b32_e32 v1, 48, v70
	v_bfi_b32 v0, -16, v8, v68
	v_add_u32_e32 v4, 0, v1
	v_mad_u64_u32 v[18:19], s[2:3], v0, s4, v[4:5]
	s_waitcnt lgkmcnt(0)
	s_barrier
	ds_read_b128 v[0:3], v18
	v_mad_u32_u24 v19, v9, s4, v4
	ds_read_b128 v[4:7], v19 offset:33792
	ds_read_b128 v[10:13], v19 offset:42240
	s_waitcnt lgkmcnt(1)
	v_mfma_f32_16x16x32_bf16 v[4:7], v[0:3], v[4:7], 0
	s_add_i32 s4, 0, 0x1bd00
	s_waitcnt lgkmcnt(0)
	v_mfma_f32_16x16x32_bf16 v[0:3], v[0:3], v[10:13], 0
	ds_read_b128 v[10:13], v18 offset:64
	ds_read_b128 v[14:17], v19 offset:33856
	s_waitcnt lgkmcnt(0)
	v_mfma_f32_16x16x32_bf16 v[4:7], v[10:13], v[14:17], v[4:7]
	ds_read_b128 v[14:17], v19 offset:42304
	s_waitcnt lgkmcnt(0)
	v_mfma_f32_16x16x32_bf16 v[0:3], v[10:13], v[14:17], v[0:3]
	ds_read_b128 v[10:13], v18 offset:128
	ds_read_b128 v[14:17], v19 offset:33920
	s_waitcnt lgkmcnt(0)
	v_mfma_f32_16x16x32_bf16 v[4:7], v[10:13], v[14:17], v[4:7]
	ds_read_b128 v[14:17], v19 offset:42368
	s_waitcnt lgkmcnt(0)
	v_mfma_f32_16x16x32_bf16 v[0:3], v[10:13], v[14:17], v[0:3]
	ds_read_b128 v[10:13], v18 offset:192
	ds_read_b128 v[14:17], v19 offset:33984
	s_waitcnt lgkmcnt(0)
	v_mfma_f32_16x16x32_bf16 v[4:7], v[10:13], v[14:17], v[4:7]
	ds_read_b128 v[14:17], v19 offset:42432
	s_waitcnt lgkmcnt(0)
	v_mfma_f32_16x16x32_bf16 v[0:3], v[10:13], v[14:17], v[0:3]
	ds_read_b128 v[10:13], v18 offset:256
	ds_read_b128 v[14:17], v19 offset:34048
	s_waitcnt lgkmcnt(0)
	v_mfma_f32_16x16x32_bf16 v[4:7], v[10:13], v[14:17], v[4:7]
	ds_read_b128 v[14:17], v19 offset:42496
	s_waitcnt lgkmcnt(0)
	v_mfma_f32_16x16x32_bf16 v[0:3], v[10:13], v[14:17], v[0:3]
	ds_read_b128 v[10:13], v18 offset:320
	ds_read_b128 v[14:17], v19 offset:34112
	s_waitcnt lgkmcnt(0)
	v_mfma_f32_16x16x32_bf16 v[4:7], v[10:13], v[14:17], v[4:7]
	ds_read_b128 v[14:17], v19 offset:42560
	s_waitcnt lgkmcnt(0)
	v_mfma_f32_16x16x32_bf16 v[0:3], v[10:13], v[14:17], v[0:3]
	ds_read_b128 v[10:13], v18 offset:384
	ds_read_b128 v[14:17], v19 offset:34176
	s_waitcnt lgkmcnt(0)
	v_mfma_f32_16x16x32_bf16 v[4:7], v[10:13], v[14:17], v[4:7]
	ds_read_b128 v[14:17], v19 offset:42624
	s_waitcnt lgkmcnt(0)
	v_mfma_f32_16x16x32_bf16 v[0:3], v[10:13], v[14:17], v[0:3]
	ds_read_b128 v[10:13], v18 offset:448
	ds_read_b128 v[14:17], v19 offset:34240
	v_lshl_add_u32 v18, v9, 2, s4
	s_waitcnt lgkmcnt(0)
	v_mfma_f32_16x16x32_bf16 v[4:7], v[10:13], v[14:17], v[4:7]
	ds_read_b128 v[14:17], v19 offset:42688
	s_waitcnt lgkmcnt(0)
	v_mfma_f32_16x16x32_bf16 v[0:3], v[10:13], v[14:17], v[0:3]
	v_lshrrev_b32_e32 v10, 2, v70
	v_and_b32_e32 v72, 12, v10
	v_or_b32_e32 v11, v72, v20
	v_cmp_le_i32_e32 vcc, v9, v11
	v_mov_b32_e32 v15, 0
	v_lshl_add_u32 v10, v11, 2, 0
	v_mov_b32_e32 v13, 0
	s_and_saveexec_b64 s[2:3], vcc
	s_cbranch_execz .LBB0_605
	v_add_u32_e32 v12, 0x1bc00, v10
	v_add_u32_e32 v13, 0x1be00, v10
	ds_read_b32 v12, v12
	ds_read_b32 v13, v13
	s_waitcnt lgkmcnt(0)
	v_sub_f32_e32 v12, v12, v13
	ds_read_b32 v13, v18
	s_waitcnt lgkmcnt(0)
	v_add_f32_e32 v12, v12, v13
	v_mul_f32_e32 v12, 0x3fb8aa3b, v12
	v_exp_f32_e32 v12, v12
	s_nop 0
	v_mul_f32_e32 v4, v4, v12
	v_cvt_pk_bf16_f32 v13, v4, s0

.LBB0_625:
	v_lshl_add_u64 v[92:93], v[64:65], 0, v[168:169]
	v_add_co_u32_e32 v96, vcc, s3, v92
	s_nop 1
	v_addc_co_u32_e32 v97, vcc, 0, v93, vcc
	v_lshl_add_u64 v[92:93], v[66:67], 0, v[168:169]
	v_add_co_u32_e32 v98, vcc, s3, v92
	s_nop 1
	v_addc_co_u32_e32 v99, vcc, 0, v93, vcc
	global_load_dwordx4 v[92:95], v[96:97], off
	global_load_dwordx4 v[244:247], v[98:99], off
	global_load_dwordx4 v[248:251], v[96:97], off offset:64
	global_load_dwordx4 v[252:255], v[98:99], off offset:64
	ds_read_b128 v[76:79], v75
	ds_read_b128 v[80:83], v75 offset:8448
	ds_read_b128 v[84:87], v75 offset:16896
	ds_read_b128 v[88:91], v75 offset:25344
	s_waitcnt vmcnt(3) lgkmcnt(3)
	v_mfma_f32_16x16x32_bf16 v[56:59], v[92:95], v[76:79], v[56:59]
	s_waitcnt lgkmcnt(2)
	v_mfma_f32_16x16x32_bf16 v[48:51], v[92:95], v[80:83], v[48:51]
	s_waitcnt lgkmcnt(1)
	v_mfma_f32_16x16x32_bf16 v[40:43], v[92:95], v[84:87], v[40:43]
	s_waitcnt lgkmcnt(0)
	v_mfma_f32_16x16x32_bf16 v[32:35], v[92:95], v[88:91], v[32:35]
	global_load_dwordx4 v[92:95], v[96:97], off offset:128
	s_waitcnt vmcnt(3)
	v_mfma_f32_16x16x32_bf16 v[60:63], v[244:247], v[76:79], v[60:63]
	v_mfma_f32_16x16x32_bf16 v[52:55], v[244:247], v[80:83], v[52:55]
	v_mfma_f32_16x16x32_bf16 v[44:47], v[244:247], v[84:87], v[44:47]
	v_mfma_f32_16x16x32_bf16 v[36:39], v[244:247], v[88:91], v[36:39]
	global_load_dwordx4 v[244:247], v[98:99], off offset:128
	ds_read_b128 v[76:79], v75 offset:64
	ds_read_b128 v[80:83], v75 offset:8512
	ds_read_b128 v[84:87], v75 offset:16960
	ds_read_b128 v[88:91], v75 offset:25408
	s_waitcnt vmcnt(3) lgkmcnt(3)
	v_mfma_f32_16x16x32_bf16 v[56:59], v[248:251], v[76:79], v[56:59]
	s_waitcnt lgkmcnt(2)
	v_mfma_f32_16x16x32_bf16 v[48:51], v[248:251], v[80:83], v[48:51]
	s_waitcnt lgkmcnt(1)
	v_mfma_f32_16x16x32_bf16 v[40:43], v[248:251], v[84:87], v[40:43]
	s_waitcnt lgkmcnt(0)
	v_mfma_f32_16x16x32_bf16 v[32:35], v[248:251], v[88:91], v[32:35]
	global_load_dwordx4 v[248:251], v[96:97], off offset:192
	s_waitcnt vmcnt(3)
	v_mfma_f32_16x16x32_bf16 v[60:63], v[252:255], v[76:79], v[60:63]
	v_mfma_f32_16x16x32_bf16 v[52:55], v[252:255], v[80:83], v[52:55]
	v_mfma_f32_16x16x32_bf16 v[44:47], v[252:255], v[84:87], v[44:47]
	v_mfma_f32_16x16x32_bf16 v[36:39], v[252:255], v[88:91], v[36:39]
	global_load_dwordx4 v[252:255], v[98:99], off offset:192
	ds_read_b128 v[76:79], v75 offset:128
	ds_read_b128 v[80:83], v75 offset:8576
	ds_read_b128 v[84:87], v75 offset:17024
	ds_read_b128 v[88:91], v75 offset:25472
	s_waitcnt vmcnt(3) lgkmcnt(3)
	v_mfma_f32_16x16x32_bf16 v[56:59], v[92:95], v[76:79], v[56:59]
	s_waitcnt lgkmcnt(2)
	v_mfma_f32_16x16x32_bf16 v[48:51], v[92:95], v[80:83], v[48:51]
	s_waitcnt lgkmcnt(1)
	v_mfma_f32_16x16x32_bf16 v[40:43], v[92:95], v[84:87], v[40:43]
	s_waitcnt lgkmcnt(0)
	v_mfma_f32_16x16x32_bf16 v[32:35], v[92:95], v[88:91], v[32:35]
	global_load_dwordx4 v[92:95], v[96:97], off offset:256
	s_waitcnt vmcnt(3)
	v_mfma_f32_16x16x32_bf16 v[60:63], v[244:247], v[76:79], v[60:63]
	v_mfma_f32_16x16x32_bf16 v[52:55], v[244:247], v[80:83], v[52:55]
	v_mfma_f32_16x16x32_bf16 v[44:47], v[244:247], v[84:87], v[44:47]
	v_mfma_f32_16x16x32_bf16 v[36:39], v[244:247], v[88:91], v[36:39]
	global_load_dwordx4 v[244:247], v[98:99], off offset:256
	ds_read_b128 v[76:79], v75 offset:192
	ds_read_b128 v[80:83], v75 offset:8640
	ds_read_b128 v[84:87], v75 offset:17088
	ds_read_b128 v[88:91], v75 offset:25536
	s_waitcnt vmcnt(3) lgkmcnt(3)
	v_mfma_f32_16x16x32_bf16 v[56:59], v[248:251], v[76:79], v[56:59]
	s_waitcnt lgkmcnt(2)
	v_mfma_f32_16x16x32_bf16 v[48:51], v[248:251], v[80:83], v[48:51]
	s_waitcnt lgkmcnt(1)
	v_mfma_f32_16x16x32_bf16 v[40:43], v[248:251], v[84:87], v[40:43]
	s_waitcnt lgkmcnt(0)
	v_mfma_f32_16x16x32_bf16 v[32:35], v[248:251], v[88:91], v[32:35]
	global_load_dwordx4 v[248:251], v[96:97], off offset:320
	s_waitcnt vmcnt(3)
	v_mfma_f32_16x16x32_bf16 v[60:63], v[252:255], v[76:79], v[60:63]
	v_mfma_f32_16x16x32_bf16 v[52:55], v[252:255], v[80:83], v[52:55]
	v_mfma_f32_16x16x32_bf16 v[44:47], v[252:255], v[84:87], v[44:47]
	v_mfma_f32_16x16x32_bf16 v[36:39], v[252:255], v[88:91], v[36:39]
	global_load_dwordx4 v[252:255], v[98:99], off offset:320
	ds_read_b128 v[76:79], v75 offset:256
	ds_read_b128 v[80:83], v75 offset:8704
	ds_read_b128 v[84:87], v75 offset:17152
	ds_read_b128 v[88:91], v75 offset:25600
	s_waitcnt vmcnt(3) lgkmcnt(3)
	v_mfma_f32_16x16x32_bf16 v[56:59], v[92:95], v[76:79], v[56:59]
	s_waitcnt lgkmcnt(2)
	v_mfma_f32_16x16x32_bf16 v[48:51], v[92:95], v[80:83], v[48:51]
	s_waitcnt lgkmcnt(1)
	v_mfma_f32_16x16x32_bf16 v[40:43], v[92:95], v[84:87], v[40:43]
	s_waitcnt lgkmcnt(0)
	v_mfma_f32_16x16x32_bf16 v[32:35], v[92:95], v[88:91], v[32:35]
	global_load_dwordx4 v[92:95], v[96:97], off offset:384
	s_waitcnt vmcnt(3)
	v_mfma_f32_16x16x32_bf16 v[60:63], v[244:247], v[76:79], v[60:63]
	v_mfma_f32_16x16x32_bf16 v[52:55], v[244:247], v[80:83], v[52:55]
	v_mfma_f32_16x16x32_bf16 v[44:47], v[244:247], v[84:87], v[44:47]
	v_mfma_f32_16x16x32_bf16 v[36:39], v[244:247], v[88:91], v[36:39]
	global_load_dwordx4 v[244:247], v[98:99], off offset:384
	ds_read_b128 v[76:79], v75 offset:320
	ds_read_b128 v[80:83], v75 offset:8768
	ds_read_b128 v[84:87], v75 offset:17216
	ds_read_b128 v[88:91], v75 offset:25664
	s_waitcnt vmcnt(3) lgkmcnt(3)
	v_mfma_f32_16x16x32_bf16 v[56:59], v[248:251], v[76:79], v[56:59]
	s_waitcnt lgkmcnt(2)
	v_mfma_f32_16x16x32_bf16 v[48:51], v[248:251], v[80:83], v[48:51]
	s_waitcnt lgkmcnt(1)
	v_mfma_f32_16x16x32_bf16 v[40:43], v[248:251], v[84:87], v[40:43]
	s_waitcnt lgkmcnt(0)
	v_mfma_f32_16x16x32_bf16 v[32:35], v[248:251], v[88:91], v[32:35]
	global_load_dwordx4 v[248:251], v[96:97], off offset:448
	s_waitcnt vmcnt(3)
	v_mfma_f32_16x16x32_bf16 v[60:63], v[252:255], v[76:79], v[60:63]
	v_mfma_f32_16x16x32_bf16 v[52:55], v[252:255], v[80:83], v[52:55]
	v_mfma_f32_16x16x32_bf16 v[44:47], v[252:255], v[84:87], v[44:47]
	v_mfma_f32_16x16x32_bf16 v[36:39], v[252:255], v[88:91], v[36:39]
	global_load_dwordx4 v[252:255], v[98:99], off offset:448
	ds_read_b128 v[76:79], v75 offset:384
	ds_read_b128 v[80:83], v75 offset:8832
	ds_read_b128 v[84:87], v75 offset:17280
	ds_read_b128 v[88:91], v75 offset:25728
	s_waitcnt vmcnt(3) lgkmcnt(3)
	v_mfma_f32_16x16x32_bf16 v[56:59], v[92:95], v[76:79], v[56:59]
	s_waitcnt lgkmcnt(2)
	v_mfma_f32_16x16x32_bf16 v[48:51], v[92:95], v[80:83], v[48:51]
	s_waitcnt lgkmcnt(1)
	v_mfma_f32_16x16x32_bf16 v[40:43], v[92:95], v[84:87], v[40:43]
	s_waitcnt lgkmcnt(0)
	v_mfma_f32_16x16x32_bf16 v[32:35], v[92:95], v[88:91], v[32:35]
	s_waitcnt vmcnt(2)
	v_mfma_f32_16x16x32_bf16 v[60:63], v[244:247], v[76:79], v[60:63]
	v_mfma_f32_16x16x32_bf16 v[52:55], v[244:247], v[80:83], v[52:55]
	v_mfma_f32_16x16x32_bf16 v[44:47], v[244:247], v[84:87], v[44:47]
	v_mfma_f32_16x16x32_bf16 v[36:39], v[244:247], v[88:91], v[36:39]
	ds_read_b128 v[76:79], v75 offset:448
	ds_read_b128 v[80:83], v75 offset:8896
	ds_read_b128 v[84:87], v75 offset:17344
	ds_read_b128 v[88:91], v75 offset:25792
	s_waitcnt vmcnt(1) lgkmcnt(3)
	v_mfma_f32_16x16x32_bf16 v[56:59], v[248:251], v[76:79], v[56:59]
	s_waitcnt lgkmcnt(2)
	v_mfma_f32_16x16x32_bf16 v[48:51], v[248:251], v[80:83], v[48:51]
	s_waitcnt lgkmcnt(1)
	v_mfma_f32_16x16x32_bf16 v[40:43], v[248:251], v[84:87], v[40:43]
	s_waitcnt lgkmcnt(0)
	v_mfma_f32_16x16x32_bf16 v[32:35], v[248:251], v[88:91], v[32:35]
	s_waitcnt vmcnt(0)
	v_mfma_f32_16x16x32_bf16 v[60:63], v[252:255], v[76:79], v[60:63]
	v_mfma_f32_16x16x32_bf16 v[52:55], v[252:255], v[80:83], v[52:55]
	v_mfma_f32_16x16x32_bf16 v[44:47], v[252:255], v[84:87], v[44:47]
	v_mfma_f32_16x16x32_bf16 v[36:39], v[252:255], v[88:91], v[36:39]
	s_movk_i32 s2, 0xe0
	v_add_u32_e32 v75, 0x200, v75
	v_lshl_add_u64 v[64:65], v[64:65], 0, s[0:1]
	v_lshl_add_u64 v[66:67], v[66:67], 0, s[0:1]
	v_lshl_add_u64 v[64:65], v[64:65], 0, s[0:1]
	v_lshl_add_u64 v[66:67], v[66:67], 0, s[0:1]
	v_lshl_add_u64 v[64:65], v[64:65], 0, s[0:1]
	v_lshl_add_u64 v[66:67], v[66:67], 0, s[0:1]
	v_lshl_add_u64 v[64:65], v[64:65], 0, s[0:1]
	v_lshl_add_u64 v[66:67], v[66:67], 0, s[0:1]
	s_cmpk_lt_u32 s2, 0xe0
	s_branch .LBB0_627

.LBB0_649:
	s_or_b64 exec, exec, s[2:3]
	v_add_u32_e32 v4, s56, v136
	s_add_i32 s2, 0, 0x1ec00
	v_or_b32_e32 v32, v145, v4
	v_lshl_add_u32 v4, v144, 2, s2
	s_waitcnt lgkmcnt(0)
	s_barrier
	ds_read_b32 v28, v4
	v_or_b32_e32 v4, s29, v144
	v_ashrrev_i32_e32 v5, 31, v4
	v_lshlrev_b64 v[4:5], 12, v[4:5]
	v_lshl_add_u64 v[4:5], s[92:93], 0, v[4:5]
	s_mov_b64 s[4:5], 0x1ac80800
	v_ashrrev_i32_e32 v33, 31, v32
	v_lshl_add_u64 v[30:31], v[4:5], 0, s[4:5]
	v_lshl_add_u64 v[4:5], v[32:33], 2, s[6:7]
	global_load_dwordx4 v[12:15], v[4:5], off
	global_load_dwordx4 v[244:247], v[4:5], off offset:64
	s_waitcnt lgkmcnt(0)
	v_pk_mul_f32 v[6:7], v[92:93], v[28:29] op_sel_hi:[1,0]
	v_pk_mul_f32 v[36:37], v[120:121], v[28:29] op_sel_hi:[1,0]
	v_or_b32_e32 v34, 16, v32
	v_ashrrev_i32_e32 v35, 31, v34
	v_pk_mul_f32 v[38:39], v[76:77], v[28:29] op_sel_hi:[1,0]
	s_add_i32 s28, s28, s69
	s_cmpk_gt_i32 s28, 0xff
	s_waitcnt vmcnt(0)
	v_pk_mul_f32 v[6:7], v[6:7], v[12:13]
	s_nop 0
	v_cvt_pk_bf16_f32 v12, v6, v7
	v_pk_mul_f32 v[6:7], v[94:95], v[28:29] op_sel_hi:[1,0]
	s_nop 0
	v_pk_mul_f32 v[6:7], v[6:7], v[14:15]
	s_nop 0
	v_cvt_pk_bf16_f32 v13, v6, v7
	v_lshlrev_b64 v[6:7], 1, v[32:33]
	v_lshl_add_u64 v[14:15], v[30:31], 0, v[6:7]
	global_store_dwordx2 v[14:15], v[12:13], off
	s_waitcnt vmcnt(1)
	v_mov_b32_e32 v12, v244
	v_mov_b32_e32 v13, v245
	v_mov_b32_e32 v14, v246
	v_mov_b32_e32 v15, v247
	global_load_dwordx4 v[244:247], v[4:5], off offset:128
	v_pk_mul_f32 v[12:13], v[36:37], v[12:13]
	s_nop 0
	v_cvt_pk_bf16_f32 v36, v12, v13
	v_pk_mul_f32 v[12:13], v[122:123], v[28:29] op_sel_hi:[1,0]
	s_nop 0
	v_pk_mul_f32 v[12:13], v[12:13], v[14:15]
	s_nop 0
	v_cvt_pk_bf16_f32 v37, v12, v13
	v_lshlrev_b64 v[12:13], 1, v[34:35]
	v_lshl_add_u64 v[14:15], v[30:31], 0, v[12:13]
	global_store_dwordx2 v[14:15], v[36:37], off
	s_waitcnt vmcnt(1)
	v_mov_b32_e32 v34, v244
	v_mov_b32_e32 v35, v245
	v_mov_b32_e32 v36, v246
	v_mov_b32_e32 v37, v247
	global_load_dwordx4 v[244:247], v[4:5], off offset:192
	v_or_b32_e32 v14, 32, v32
	v_ashrrev_i32_e32 v15, 31, v14
	v_lshlrev_b64 v[14:15], 1, v[14:15]
	v_pk_mul_f32 v[34:35], v[38:39], v[34:35]
	v_pk_mul_f32 v[38:39], v[78:79], v[28:29] op_sel_hi:[1,0]
	v_cvt_pk_bf16_f32 v34, v34, v35
	v_pk_mul_f32 v[36:37], v[38:39], v[36:37]
	v_pk_mul_f32 v[38:39], v[64:65], v[28:29] op_sel_hi:[1,0]
	v_cvt_pk_bf16_f32 v35, v36, v37
	v_lshl_add_u64 v[36:37], v[30:31], 0, v[14:15]
	global_store_dwordx2 v[36:37], v[34:35], off
	v_or_b32_e32 v36, 48, v32
	s_waitcnt vmcnt(1)
	v_mov_b32_e32 v32, v244
	v_mov_b32_e32 v33, v245
	v_mov_b32_e32 v34, v246
	v_mov_b32_e32 v35, v247
	global_load_dwordx4 v[244:247], v[4:5], off
	v_pk_mul_f32 v[28:29], v[66:67], v[28:29] op_sel_hi:[1,0]
	v_ashrrev_i32_e32 v37, 31, v36
	v_pk_mul_f32 v[32:33], v[38:39], v[32:33]
	v_pk_mul_f32 v[28:29], v[28:29], v[34:35]
	v_cvt_pk_bf16_f32 v32, v32, v33
	v_cvt_pk_bf16_f32 v33, v28, v29
	v_lshlrev_b64 v[28:29], 1, v[36:37]
	v_lshl_add_u64 v[30:31], v[30:31], 0, v[28:29]
	global_store_dwordx2 v[30:31], v[32:33], off
	v_lshl_add_u32 v30, v146, 2, s2
	ds_read_b32 v34, v30
	v_or_b32_e32 v30, s29, v146
	v_ashrrev_i32_e32 v31, 31, v30
	v_lshlrev_b64 v[30:31], 12, v[30:31]
	v_lshl_add_u64 v[30:31], s[92:93], 0, v[30:31]
	v_lshl_add_u64 v[36:37], v[30:31], 0, s[4:5]
	s_waitcnt vmcnt(1)
	v_mov_b32_e32 v30, v244
	v_mov_b32_e32 v31, v245
	v_mov_b32_e32 v32, v246
	v_mov_b32_e32 v33, v247
	global_load_dwordx4 v[244:247], v[4:5], off offset:64
	s_waitcnt lgkmcnt(0)
	v_pk_mul_f32 v[38:39], v[68:69], v[34:35] op_sel_hi:[1,0]
	v_pk_mul_f32 v[30:31], v[38:39], v[30:31]
	v_pk_mul_f32 v[38:39], v[70:71], v[34:35] op_sel_hi:[1,0]
	v_cvt_pk_bf16_f32 v30, v30, v31
	v_pk_mul_f32 v[32:33], v[38:39], v[32:33]
	v_pk_mul_f32 v[38:39], v[88:89], v[34:35] op_sel_hi:[1,0]
	v_cvt_pk_bf16_f32 v31, v32, v33
	v_lshl_add_u64 v[32:33], v[36:37], 0, v[6:7]
	global_store_dwordx2 v[32:33], v[30:31], off
	s_waitcnt vmcnt(1)
	v_mov_b32_e32 v30, v244
	v_mov_b32_e32 v31, v245
	v_mov_b32_e32 v32, v246
	v_mov_b32_e32 v33, v247
	global_load_dwordx4 v[244:247], v[4:5], off offset:128
	v_pk_mul_f32 v[30:31], v[38:39], v[30:31]
	v_pk_mul_f32 v[38:39], v[90:91], v[34:35] op_sel_hi:[1,0]
	v_cvt_pk_bf16_f32 v30, v30, v31
	v_pk_mul_f32 v[32:33], v[38:39], v[32:33]
	v_pk_mul_f32 v[38:39], v[44:45], v[34:35] op_sel_hi:[1,0]
	v_cvt_pk_bf16_f32 v31, v32, v33
	v_lshl_add_u64 v[32:33], v[36:37], 0, v[12:13]
	global_store_dwordx2 v[32:33], v[30:31], off
	s_waitcnt vmcnt(1)
	v_mov_b32_e32 v30, v244
	v_mov_b32_e32 v31, v245
	v_mov_b32_e32 v32, v246
	v_mov_b32_e32 v33, v247
	global_load_dwordx4 v[244:247], v[4:5], off offset:192
	v_pk_mul_f32 v[30:31], v[38:39], v[30:31]
	v_pk_mul_f32 v[38:39], v[46:47], v[34:35] op_sel_hi:[1,0]
	v_cvt_pk_bf16_f32 v30, v30, v31
	v_pk_mul_f32 v[32:33], v[38:39], v[32:33]
	v_pk_mul_f32 v[38:39], v[56:57], v[34:35] op_sel_hi:[1,0]
	v_cvt_pk_bf16_f32 v31, v32, v33
	v_lshl_add_u64 v[32:33], v[36:37], 0, v[14:15]
	global_store_dwordx2 v[32:33], v[30:31], off
	s_waitcnt vmcnt(1)
	v_mov_b32_e32 v30, v244
	v_mov_b32_e32 v31, v245
	v_mov_b32_e32 v32, v246
	v_mov_b32_e32 v33, v247
	global_load_dwordx4 v[244:247], v[4:5], off
	v_pk_mul_f32 v[34:35], v[96:97], v[34:35] op_sel_hi:[1,0]
	v_pk_mul_f32 v[30:31], v[38:39], v[30:31]
	v_pk_mul_f32 v[32:33], v[34:35], v[32:33]
	v_cvt_pk_bf16_f32 v30, v30, v31
	v_cvt_pk_bf16_f32 v31, v32, v33
	v_lshl_add_u64 v[32:33], v[36:37], 0, v[28:29]
	global_store_dwordx2 v[32:33], v[30:31], off
	v_lshl_add_u32 v30, v147, 2, s2
	ds_read_b32 v34, v30
	v_or_b32_e32 v30, s29, v147
	v_ashrrev_i32_e32 v31, 31, v30
	v_lshlrev_b64 v[30:31], 12, v[30:31]
	v_lshl_add_u64 v[30:31], s[92:93], 0, v[30:31]
	v_lshl_add_u64 v[36:37], v[30:31], 0, s[4:5]
	s_waitcnt vmcnt(1)
	v_mov_b32_e32 v30, v244
	v_mov_b32_e32 v31, v245
	v_mov_b32_e32 v32, v246
	v_mov_b32_e32 v33, v247
	global_load_dwordx4 v[244:247], v[4:5], off offset:64
	s_waitcnt lgkmcnt(0)
	v_pk_mul_f32 v[38:39], v[58:59], v[34:35] op_sel_hi:[1,0]
	v_pk_mul_f32 v[24:25], v[24:25], v[34:35] op_sel_hi:[1,0]
	v_pk_mul_f32 v[30:31], v[38:39], v[30:31]
	v_pk_mul_f32 v[38:39], v[60:61], v[34:35] op_sel_hi:[1,0]
	v_cvt_pk_bf16_f32 v30, v30, v31
	v_pk_mul_f32 v[32:33], v[38:39], v[32:33]
	v_pk_mul_f32 v[38:39], v[48:49], v[34:35] op_sel_hi:[1,0]
	v_cvt_pk_bf16_f32 v31, v32, v33
	v_lshl_add_u64 v[32:33], v[36:37], 0, v[6:7]
	global_store_dwordx2 v[32:33], v[30:31], off
	s_waitcnt vmcnt(1)
	v_mov_b32_e32 v30, v244
	v_mov_b32_e32 v31, v245
	v_mov_b32_e32 v32, v246
	v_mov_b32_e32 v33, v247
	global_load_dwordx4 v[244:247], v[4:5], off offset:128
	v_pk_mul_f32 v[30:31], v[38:39], v[30:31]
	v_pk_mul_f32 v[38:39], v[50:51], v[34:35] op_sel_hi:[1,0]
	v_cvt_pk_bf16_f32 v30, v30, v31
	v_pk_mul_f32 v[32:33], v[38:39], v[32:33]
	s_nop 0
	v_cvt_pk_bf16_f32 v31, v32, v33
	v_lshl_add_u64 v[32:33], v[36:37], 0, v[12:13]
	global_store_dwordx2 v[32:33], v[30:31], off
	s_waitcnt vmcnt(1)
	v_mov_b32_e32 v30, v244
	v_mov_b32_e32 v31, v245
	v_mov_b32_e32 v32, v246
	v_mov_b32_e32 v33, v247
	global_load_dwordx4 v[244:247], v[4:5], off offset:192
	v_pk_mul_f32 v[24:25], v[24:25], v[30:31]
	v_pk_mul_f32 v[30:31], v[40:41], v[34:35] op_sel_hi:[1,0]
	v_cvt_pk_bf16_f32 v24, v24, v25
	v_pk_mul_f32 v[30:31], v[30:31], v[32:33]
	s_nop 0
	v_cvt_pk_bf16_f32 v25, v30, v31
	v_lshl_add_u64 v[30:31], v[36:37], 0, v[14:15]
	global_store_dwordx2 v[30:31], v[24:25], off
	s_waitcnt vmcnt(1)
	v_mov_b32_e32 v30, v244
	v_mov_b32_e32 v31, v245
	v_mov_b32_e32 v32, v246
	v_mov_b32_e32 v33, v247
	global_load_dwordx4 v[244:247], v[4:5], off
	v_pk_mul_f32 v[24:25], v[26:27], v[34:35] op_sel_hi:[1,0]
	v_pk_mul_f32 v[26:27], v[42:43], v[34:35] op_sel_hi:[1,0]
	v_pk_mul_f32 v[24:25], v[24:25], v[30:31]
	v_pk_mul_f32 v[26:27], v[26:27], v[32:33]
	v_cvt_pk_bf16_f32 v24, v24, v25
	v_cvt_pk_bf16_f32 v25, v26, v27
	v_lshl_add_u64 v[26:27], v[36:37], 0, v[28:29]
	global_store_dwordx2 v[26:27], v[24:25], off
	s_waitcnt vmcnt(1)
	v_mov_b32_e32 v30, v244
	v_mov_b32_e32 v31, v245
	v_mov_b32_e32 v32, v246
	v_mov_b32_e32 v33, v247
	global_load_dwordx4 v[244:247], v[4:5], off offset:64
	v_lshl_add_u32 v24, v148, 2, s2
	ds_read_b32 v24, v24
	v_or_b32_e32 v26, s29, v148
	v_ashrrev_i32_e32 v27, 31, v26
	v_lshlrev_b64 v[26:27], 12, v[26:27]
	v_lshl_add_u64 v[26:27], s[92:93], 0, v[26:27]
	s_waitcnt lgkmcnt(0)
	v_pk_mul_f32 v[16:17], v[16:17], v[24:25] op_sel_hi:[1,0]
	v_pk_mul_f32 v[18:19], v[18:19], v[24:25] op_sel_hi:[1,0]
	v_lshl_add_u64 v[26:27], v[26:27], 0, s[4:5]
	v_lshl_add_u64 v[6:7], v[26:27], 0, v[6:7]
	v_lshl_add_u64 v[12:13], v[26:27], 0, v[12:13]
	v_pk_mul_f32 v[0:1], v[0:1], v[24:25] op_sel_hi:[1,0]
	v_pk_mul_f32 v[2:3], v[2:3], v[24:25] op_sel_hi:[1,0]
	v_pk_mul_f32 v[16:17], v[16:17], v[30:31]
	v_pk_mul_f32 v[18:19], v[18:19], v[32:33]
	v_cvt_pk_bf16_f32 v16, v16, v17
	v_cvt_pk_bf16_f32 v17, v18, v19
	global_store_dwordx2 v[6:7], v[16:17], off
	s_waitcnt vmcnt(1)
	v_mov_b32_e32 v16, v244
	v_mov_b32_e32 v17, v245
	v_mov_b32_e32 v18, v246
	v_mov_b32_e32 v19, v247
	global_load_dwordx4 v[244:247], v[4:5], off offset:128
	v_pk_mul_f32 v[6:7], v[20:21], v[24:25] op_sel_hi:[1,0]
	v_pk_mul_f32 v[6:7], v[6:7], v[16:17]
	v_pk_mul_f32 v[16:17], v[22:23], v[24:25] op_sel_hi:[1,0]
	v_cvt_pk_bf16_f32 v6, v6, v7
	v_pk_mul_f32 v[16:17], v[16:17], v[18:19]
	s_nop 0
	v_cvt_pk_bf16_f32 v7, v16, v17
	global_store_dwordx2 v[12:13], v[6:7], off
	s_waitcnt vmcnt(1)
	v_mov_b32_e32 v16, v244
	v_mov_b32_e32 v17, v245
	v_mov_b32_e32 v18, v246
	v_mov_b32_e32 v19, v247
	global_load_dwordx4 v[244:247], v[4:5], off offset:192
	v_pk_mul_f32 v[6:7], v[8:9], v[24:25] op_sel_hi:[1,0]
	v_pk_mul_f32 v[8:9], v[10:11], v[24:25] op_sel_hi:[1,0]
	v_pk_mul_f32 v[6:7], v[6:7], v[16:17]
	v_pk_mul_f32 v[8:9], v[8:9], v[18:19]
	v_cvt_pk_bf16_f32 v6, v6, v7
	v_cvt_pk_bf16_f32 v7, v8, v9
	v_lshl_add_u64 v[8:9], v[26:27], 0, v[14:15]
	global_store_dwordx2 v[8:9], v[6:7], off
	s_waitcnt vmcnt(1)
	v_mov_b32_e32 v4, v244
	v_mov_b32_e32 v5, v245
	v_mov_b32_e32 v6, v246
	v_mov_b32_e32 v7, v247
	v_pk_mul_f32 v[0:1], v[0:1], v[4:5]
	v_pk_mul_f32 v[2:3], v[2:3], v[6:7]
	v_cvt_pk_bf16_f32 v0, v0, v1
	v_cvt_pk_bf16_f32 v1, v2, v3
	v_lshl_add_u64 v[2:3], v[26:27], 0, v[28:29]
	global_store_dwordx2 v[2:3], v[0:1], off
	s_barrier
	s_cbranch_scc1 .LBB0_918
